# P8 epilogue: 8-deep register-ring prefetch of the X1B residual loads with counted vmcnt (was 16 serialized round trips)
# speedup vs baseline: 1.0016x; 1.0016x over previous
.LBB0_941:
	s_lshl_b32 s2, s86, 8
	s_add_i32 s3, s2, 0xffffe000
	s_ashr_i32 s3, s3, 10
	s_add_i32 s3, s3, 1
	s_cmp_gt_i32 s86, 31
	s_cselect_b32 s21, s3, 0
	s_ashr_i32 s3, s2, 31
	s_lshl_b64 s[26:27], s[2:3], 14
	s_mul_hi_i32 s3, s21, 0x18000
	s_mul_i32 s21, s21, 0x18000
	s_add_u32 s34, s76, s21
	s_addc_u32 s35, s77, s3
	s_mul_i32 s3, s86, 0x208000
	v_lshl_or_b32 v128, s30, 8, v183
	s_mul_hi_i32 s21, s2, 0x2080
	s_add_u32 s2, s96, s3
	v_ashrrev_i32_e32 v129, 31, v128
	s_addc_u32 s3, s97, s21
	v_lshl_add_u64 v[180:181], v[128:129], 1, s[2:3]
	v_lshl_add_u64 v[196:197], v[180:181], 0, v[160:161]
	s_nop 0
	v_lshlrev_b64 v[178:179], 2, v[128:129]
	v_lshl_add_u64 v[192:193], s[34:35], 0, v[178:179]
	global_load_dwordx4 v[132:135], v[192:193], off
	global_load_dwordx4 v[128:131], v[192:193], off offset:16
	ds_bpermute_b32 v194, v184, v124
	ds_bpermute_b32 v195, v184, v125
	ds_bpermute_b32 v198, v184, v126
	ds_bpermute_b32 v199, v184, v127
	ds_bpermute_b32 v200, v184, v120
	ds_bpermute_b32 v201, v184, v121
	ds_bpermute_b32 v202, v184, v122
	ds_bpermute_b32 v203, v184, v123
	s_add_u32 s2, s48, s26
	s_addc_u32 s3, s49, s27
	global_load_dwordx4 v[120:123], v[192:193], off offset:528
	global_load_dwordx4 v[124:127], v[192:193], off offset:512
	v_lshl_add_u64 v[244:245], v[180:181], 0, v[160:161]
	global_load_dwordx4 v[212:215], v[244:245], off nt
	global_load_dwordx4 v[216:219], v[244:245], off offset:256 nt
	v_lshl_add_u64 v[244:245], v[180:181], 0, v[162:163]
	global_load_dwordx4 v[220:223], v[244:245], off nt
	global_load_dwordx4 v[224:227], v[244:245], off offset:256 nt
	v_lshl_add_u64 v[244:245], v[180:181], 0, v[164:165]
	global_load_dwordx4 v[228:231], v[244:245], off nt
	global_load_dwordx4 v[232:235], v[244:245], off offset:256 nt
	v_lshl_add_u64 v[244:245], v[180:181], 0, v[166:167]
	global_load_dwordx4 v[236:239], v[244:245], off nt
	global_load_dwordx4 v[240:243], v[244:245], off offset:256 nt
	v_lshl_add_u64 v[178:179], s[2:3], 0, v[178:179]
	v_lshl_add_u64 v[204:205], v[178:179], 0, v[144:145]
	ds_bpermute_b32 v116, v184, v116
	ds_bpermute_b32 v117, v184, v117
	ds_bpermute_b32 v118, v184, v118
	ds_bpermute_b32 v119, v184, v119
	ds_bpermute_b32 v108, v184, v108
	ds_bpermute_b32 v109, v184, v109
	ds_bpermute_b32 v110, v184, v110
	ds_bpermute_b32 v111, v184, v111
	ds_bpermute_b32 v100, v184, v100
	ds_bpermute_b32 v101, v184, v101
	ds_bpermute_b32 v102, v184, v102
	ds_bpermute_b32 v103, v184, v103
	ds_bpermute_b32 v92, v184, v92
	ds_bpermute_b32 v93, v184, v93
	ds_bpermute_b32 v94, v184, v94
	ds_bpermute_b32 v95, v184, v95
	ds_bpermute_b32 v84, v184, v84
	ds_bpermute_b32 v85, v184, v85
	ds_bpermute_b32 v86, v184, v86
	ds_bpermute_b32 v87, v184, v87
	ds_bpermute_b32 v76, v184, v76
	ds_bpermute_b32 v77, v184, v77
	ds_bpermute_b32 v78, v184, v78
	ds_bpermute_b32 v79, v184, v79
	ds_bpermute_b32 v68, v184, v68
	ds_bpermute_b32 v69, v184, v69
	ds_bpermute_b32 v70, v184, v70
	ds_bpermute_b32 v71, v184, v71
	ds_bpermute_b32 v60, v184, v60
	ds_bpermute_b32 v61, v184, v61
	ds_bpermute_b32 v62, v184, v62
	ds_bpermute_b32 v63, v184, v63
	ds_bpermute_b32 v52, v184, v52
	ds_bpermute_b32 v53, v184, v53
	ds_bpermute_b32 v54, v184, v54
	ds_bpermute_b32 v55, v184, v55
	ds_bpermute_b32 v44, v184, v44
	ds_bpermute_b32 v45, v184, v45
	ds_bpermute_b32 v46, v184, v46
	ds_bpermute_b32 v47, v184, v47
	ds_bpermute_b32 v36, v184, v36
	ds_bpermute_b32 v37, v184, v37
	ds_bpermute_b32 v38, v184, v38
	ds_bpermute_b32 v39, v184, v39
	ds_bpermute_b32 v28, v184, v28
	ds_bpermute_b32 v29, v184, v29
	ds_bpermute_b32 v30, v184, v30
	ds_bpermute_b32 v31, v184, v31
	ds_bpermute_b32 v20, v184, v20
	ds_bpermute_b32 v21, v184, v21
	ds_bpermute_b32 v22, v184, v22
	ds_bpermute_b32 v23, v184, v23
	ds_bpermute_b32 v12, v184, v12
	ds_bpermute_b32 v13, v184, v13
	ds_bpermute_b32 v14, v184, v14
	ds_bpermute_b32 v15, v184, v15
	ds_bpermute_b32 v4, v184, v4
	ds_bpermute_b32 v5, v184, v5
	ds_bpermute_b32 v6, v184, v6
	ds_bpermute_b32 v7, v184, v7
	s_andn2_b64 vcc, exec, s[28:29]
	s_mov_b64 s[2:3], -1
	s_waitcnt vmcnt(7)
	v_lshlrev_b32_e32 v192, 16, v212
	v_and_b32_e32 v193, 0xffff0000, v212
	v_lshlrev_b32_e32 v206, 16, v213
	v_and_b32_e32 v207, 0xffff0000, v213
	v_lshlrev_b32_e32 v208, 16, v214
	v_and_b32_e32 v209, 0xffff0000, v214
	v_lshlrev_b32_e32 v210, 16, v215
	v_and_b32_e32 v211, 0xffff0000, v215
	v_lshl_add_u64 v[244:245], v[180:181], 0, v[168:169]
	global_load_dwordx4 v[212:215], v[244:245], off nt
	s_waitcnt lgkmcnt(14)
	v_pk_fma_f32 v[188:189], v[132:133], v[194:195], v[192:193]
	v_pk_fma_f32 v[190:191], v[134:135], v[198:199], v[206:207]
	v_pk_fma_f32 v[192:193], v[128:129], v[200:201], v[208:209]
	v_pk_fma_f32 v[194:195], v[130:131], v[202:203], v[210:211]
	global_store_dwordx4 v[204:205], v[188:191], off
	global_store_dwordx4 v[204:205], v[192:195], off offset:16
	s_nop 0
	ds_bpermute_b32 v192, v184, v112
	ds_bpermute_b32 v193, v184, v113
	ds_bpermute_b32 v194, v184, v114
	ds_bpermute_b32 v195, v184, v115
	v_lshl_add_u64 v[196:197], v[180:181], 0, v[162:163]
	s_waitcnt vmcnt(9)
	v_lshlrev_b32_e32 v112, 16, v216
	v_and_b32_e32 v113, 0xffff0000, v216
	v_lshlrev_b32_e32 v114, 16, v217
	v_and_b32_e32 v115, 0xffff0000, v217
	v_lshlrev_b32_e32 v188, 16, v218
	v_and_b32_e32 v189, 0xffff0000, v218
	v_lshlrev_b32_e32 v190, 16, v219
	v_and_b32_e32 v191, 0xffff0000, v219
	global_load_dwordx4 v[216:219], v[244:245], off offset:256 nt
	v_pk_fma_f32 v[114:115], v[126:127], v[118:119], v[114:115]
	v_pk_fma_f32 v[112:113], v[124:125], v[116:117], v[112:113]
	s_waitcnt lgkmcnt(0)
	v_pk_fma_f32 v[118:119], v[122:123], v[194:195], v[190:191]
	v_pk_fma_f32 v[116:117], v[120:121], v[192:193], v[188:189]
	global_store_dwordx4 v[204:205], v[112:115], off offset:512
	global_store_dwordx4 v[204:205], v[116:119], off offset:528
	s_nop 0
	ds_bpermute_b32 v116, v184, v104
	ds_bpermute_b32 v117, v184, v105
	ds_bpermute_b32 v118, v184, v106
	ds_bpermute_b32 v119, v184, v107
	v_lshl_add_u64 v[188:189], v[178:179], 0, v[146:147]
	s_waitcnt vmcnt(11)
	v_lshlrev_b32_e32 v104, 16, v220
	v_and_b32_e32 v105, 0xffff0000, v220
	v_lshlrev_b32_e32 v106, 16, v221
	v_and_b32_e32 v107, 0xffff0000, v221
	v_lshlrev_b32_e32 v112, 16, v222
	v_and_b32_e32 v113, 0xffff0000, v222
	v_lshlrev_b32_e32 v114, 16, v223
	v_and_b32_e32 v115, 0xffff0000, v223
	v_lshl_add_u64 v[244:245], v[180:181], 0, v[170:171]
	global_load_dwordx4 v[220:223], v[244:245], off nt
	v_pk_fma_f32 v[106:107], v[134:135], v[110:111], v[106:107]
	v_pk_fma_f32 v[104:105], v[132:133], v[108:109], v[104:105]
	s_waitcnt lgkmcnt(0)
	v_pk_fma_f32 v[110:111], v[130:131], v[118:119], v[114:115]
	v_pk_fma_f32 v[108:109], v[128:129], v[116:117], v[112:113]
	global_store_dwordx4 v[188:189], v[104:107], off
	global_store_dwordx4 v[188:189], v[108:111], off offset:16
	s_nop 0
	ds_bpermute_b32 v108, v184, v96
	ds_bpermute_b32 v109, v184, v97
	ds_bpermute_b32 v110, v184, v98
	ds_bpermute_b32 v111, v184, v99
	v_lshl_add_u64 v[112:113], v[180:181], 0, v[164:165]
	s_waitcnt vmcnt(13)
	v_lshlrev_b32_e32 v96, 16, v224
	v_and_b32_e32 v97, 0xffff0000, v224
	v_lshlrev_b32_e32 v98, 16, v225
	v_and_b32_e32 v99, 0xffff0000, v225
	v_lshlrev_b32_e32 v104, 16, v226
	v_and_b32_e32 v105, 0xffff0000, v226
	v_lshlrev_b32_e32 v106, 16, v227
	v_and_b32_e32 v107, 0xffff0000, v227
	global_load_dwordx4 v[224:227], v[244:245], off offset:256 nt
	v_pk_fma_f32 v[98:99], v[126:127], v[102:103], v[98:99]
	v_pk_fma_f32 v[96:97], v[124:125], v[100:101], v[96:97]
	s_waitcnt lgkmcnt(0)
	v_pk_fma_f32 v[102:103], v[122:123], v[110:111], v[106:107]
	v_pk_fma_f32 v[100:101], v[120:121], v[108:109], v[104:105]
	global_store_dwordx4 v[188:189], v[96:99], off offset:512
	global_store_dwordx4 v[188:189], v[100:103], off offset:528
	s_nop 0
	ds_bpermute_b32 v100, v184, v88
	ds_bpermute_b32 v101, v184, v89
	ds_bpermute_b32 v102, v184, v90
	ds_bpermute_b32 v103, v184, v91
	v_lshl_add_u64 v[104:105], v[178:179], 0, v[148:149]
	s_waitcnt vmcnt(15)
	v_lshlrev_b32_e32 v88, 16, v228
	v_and_b32_e32 v89, 0xffff0000, v228
	v_lshlrev_b32_e32 v90, 16, v229
	v_and_b32_e32 v91, 0xffff0000, v229
	v_lshlrev_b32_e32 v96, 16, v230
	v_and_b32_e32 v97, 0xffff0000, v230
	v_lshlrev_b32_e32 v98, 16, v231
	v_and_b32_e32 v99, 0xffff0000, v231
	v_lshl_add_u64 v[244:245], v[180:181], 0, v[172:173]
	global_load_dwordx4 v[228:231], v[244:245], off nt
	v_pk_fma_f32 v[90:91], v[134:135], v[94:95], v[90:91]
	v_pk_fma_f32 v[88:89], v[132:133], v[92:93], v[88:89]
	s_waitcnt lgkmcnt(0)
	v_pk_fma_f32 v[94:95], v[130:131], v[102:103], v[98:99]
	v_pk_fma_f32 v[92:93], v[128:129], v[100:101], v[96:97]
	global_store_dwordx4 v[104:105], v[88:91], off
	global_store_dwordx4 v[104:105], v[92:95], off offset:16
	s_nop 0
	ds_bpermute_b32 v92, v184, v80
	ds_bpermute_b32 v93, v184, v81
	ds_bpermute_b32 v94, v184, v82
	ds_bpermute_b32 v95, v184, v83
	v_lshl_add_u64 v[96:97], v[180:181], 0, v[166:167]
	s_waitcnt vmcnt(17)
	v_lshlrev_b32_e32 v80, 16, v232
	v_and_b32_e32 v81, 0xffff0000, v232
	v_lshlrev_b32_e32 v82, 16, v233
	v_and_b32_e32 v83, 0xffff0000, v233
	v_lshlrev_b32_e32 v88, 16, v234
	v_and_b32_e32 v89, 0xffff0000, v234
	v_lshlrev_b32_e32 v90, 16, v235
	v_and_b32_e32 v91, 0xffff0000, v235
	global_load_dwordx4 v[232:235], v[244:245], off offset:256 nt
	v_pk_fma_f32 v[82:83], v[126:127], v[86:87], v[82:83]
	v_pk_fma_f32 v[80:81], v[124:125], v[84:85], v[80:81]
	s_waitcnt lgkmcnt(0)
	v_pk_fma_f32 v[86:87], v[122:123], v[94:95], v[90:91]
	v_pk_fma_f32 v[84:85], v[120:121], v[92:93], v[88:89]
	global_store_dwordx4 v[104:105], v[80:83], off offset:512
	global_store_dwordx4 v[104:105], v[84:87], off offset:528
	s_nop 0
	ds_bpermute_b32 v84, v184, v72
	ds_bpermute_b32 v85, v184, v73
	ds_bpermute_b32 v86, v184, v74
	ds_bpermute_b32 v87, v184, v75
	v_lshl_add_u64 v[88:89], v[178:179], 0, v[150:151]
	s_waitcnt vmcnt(19)
	v_lshlrev_b32_e32 v72, 16, v236
	v_and_b32_e32 v73, 0xffff0000, v236
	v_lshlrev_b32_e32 v74, 16, v237
	v_and_b32_e32 v75, 0xffff0000, v237
	v_lshlrev_b32_e32 v80, 16, v238
	v_and_b32_e32 v81, 0xffff0000, v238
	v_lshlrev_b32_e32 v82, 16, v239
	v_and_b32_e32 v83, 0xffff0000, v239
	v_lshl_add_u64 v[244:245], v[180:181], 0, v[174:175]
	global_load_dwordx4 v[236:239], v[244:245], off nt
	v_pk_fma_f32 v[74:75], v[134:135], v[78:79], v[74:75]
	v_pk_fma_f32 v[72:73], v[132:133], v[76:77], v[72:73]
	s_waitcnt lgkmcnt(0)
	v_pk_fma_f32 v[78:79], v[130:131], v[86:87], v[82:83]
	v_pk_fma_f32 v[76:77], v[128:129], v[84:85], v[80:81]
	global_store_dwordx4 v[88:89], v[72:75], off
	global_store_dwordx4 v[88:89], v[76:79], off offset:16
	s_nop 0
	ds_bpermute_b32 v76, v184, v64
	ds_bpermute_b32 v77, v184, v65
	ds_bpermute_b32 v78, v184, v66
	ds_bpermute_b32 v79, v184, v67
	v_lshl_add_u64 v[80:81], v[180:181], 0, v[168:169]
	s_waitcnt vmcnt(21)
	v_lshlrev_b32_e32 v64, 16, v240
	v_and_b32_e32 v65, 0xffff0000, v240
	v_lshlrev_b32_e32 v66, 16, v241
	v_and_b32_e32 v67, 0xffff0000, v241
	v_lshlrev_b32_e32 v72, 16, v242
	v_and_b32_e32 v73, 0xffff0000, v242
	v_lshlrev_b32_e32 v74, 16, v243
	v_and_b32_e32 v75, 0xffff0000, v243
	global_load_dwordx4 v[240:243], v[244:245], off offset:256 nt
	v_pk_fma_f32 v[66:67], v[126:127], v[70:71], v[66:67]
	v_pk_fma_f32 v[64:65], v[124:125], v[68:69], v[64:65]
	s_waitcnt lgkmcnt(0)
	v_pk_fma_f32 v[70:71], v[122:123], v[78:79], v[74:75]
	v_pk_fma_f32 v[68:69], v[120:121], v[76:77], v[72:73]
	global_store_dwordx4 v[88:89], v[64:67], off offset:512
	global_store_dwordx4 v[88:89], v[68:71], off offset:528
	s_nop 0
	ds_bpermute_b32 v68, v184, v56
	ds_bpermute_b32 v69, v184, v57
	ds_bpermute_b32 v70, v184, v58
	ds_bpermute_b32 v71, v184, v59
	v_lshl_add_u64 v[72:73], v[178:179], 0, v[152:153]
	s_waitcnt vmcnt(23)
	v_lshlrev_b32_e32 v56, 16, v212
	v_and_b32_e32 v57, 0xffff0000, v212
	v_lshlrev_b32_e32 v58, 16, v213
	v_and_b32_e32 v59, 0xffff0000, v213
	v_lshlrev_b32_e32 v64, 16, v214
	v_and_b32_e32 v65, 0xffff0000, v214
	v_lshlrev_b32_e32 v66, 16, v215
	v_and_b32_e32 v67, 0xffff0000, v215
	v_pk_fma_f32 v[58:59], v[134:135], v[62:63], v[58:59]
	v_pk_fma_f32 v[56:57], v[132:133], v[60:61], v[56:57]
	s_waitcnt lgkmcnt(0)
	v_pk_fma_f32 v[62:63], v[130:131], v[70:71], v[66:67]
	v_pk_fma_f32 v[60:61], v[128:129], v[68:69], v[64:65]
	global_store_dwordx4 v[72:73], v[56:59], off
	global_store_dwordx4 v[72:73], v[60:63], off offset:16
	s_nop 0
	ds_bpermute_b32 v60, v184, v48
	ds_bpermute_b32 v61, v184, v49
	ds_bpermute_b32 v62, v184, v50
	ds_bpermute_b32 v63, v184, v51
	v_lshl_add_u64 v[64:65], v[180:181], 0, v[170:171]
	s_waitcnt vmcnt(22)
	v_lshlrev_b32_e32 v48, 16, v216
	v_and_b32_e32 v49, 0xffff0000, v216
	v_lshlrev_b32_e32 v50, 16, v217
	v_and_b32_e32 v51, 0xffff0000, v217
	v_lshlrev_b32_e32 v56, 16, v218
	v_and_b32_e32 v57, 0xffff0000, v218
	v_lshlrev_b32_e32 v58, 16, v219
	v_and_b32_e32 v59, 0xffff0000, v219
	v_pk_fma_f32 v[50:51], v[126:127], v[54:55], v[50:51]
	v_pk_fma_f32 v[48:49], v[124:125], v[52:53], v[48:49]
	s_waitcnt lgkmcnt(0)
	v_pk_fma_f32 v[54:55], v[122:123], v[62:63], v[58:59]
	v_pk_fma_f32 v[52:53], v[120:121], v[60:61], v[56:57]
	global_store_dwordx4 v[72:73], v[48:51], off offset:512
	global_store_dwordx4 v[72:73], v[52:55], off offset:528
	s_nop 0
	ds_bpermute_b32 v52, v184, v40
	ds_bpermute_b32 v53, v184, v41
	ds_bpermute_b32 v54, v184, v42
	ds_bpermute_b32 v55, v184, v43
	v_lshl_add_u64 v[56:57], v[178:179], 0, v[154:155]
	s_waitcnt vmcnt(21)
	v_lshlrev_b32_e32 v40, 16, v220
	v_and_b32_e32 v41, 0xffff0000, v220
	v_lshlrev_b32_e32 v42, 16, v221
	v_and_b32_e32 v43, 0xffff0000, v221
	v_lshlrev_b32_e32 v48, 16, v222
	v_and_b32_e32 v49, 0xffff0000, v222
	v_lshlrev_b32_e32 v50, 16, v223
	v_and_b32_e32 v51, 0xffff0000, v223
	v_pk_fma_f32 v[42:43], v[134:135], v[46:47], v[42:43]
	v_pk_fma_f32 v[40:41], v[132:133], v[44:45], v[40:41]
	s_waitcnt lgkmcnt(0)
	v_pk_fma_f32 v[46:47], v[130:131], v[54:55], v[50:51]
	v_pk_fma_f32 v[44:45], v[128:129], v[52:53], v[48:49]
	global_store_dwordx4 v[56:57], v[40:43], off
	global_store_dwordx4 v[56:57], v[44:47], off offset:16
	s_nop 0
	ds_bpermute_b32 v44, v184, v32
	ds_bpermute_b32 v45, v184, v33
	ds_bpermute_b32 v46, v184, v34
	ds_bpermute_b32 v47, v184, v35
	v_lshl_add_u64 v[48:49], v[180:181], 0, v[172:173]
	s_waitcnt vmcnt(20)
	v_lshlrev_b32_e32 v32, 16, v224
	v_and_b32_e32 v33, 0xffff0000, v224
	v_lshlrev_b32_e32 v34, 16, v225
	v_and_b32_e32 v35, 0xffff0000, v225
	v_lshlrev_b32_e32 v40, 16, v226
	v_and_b32_e32 v41, 0xffff0000, v226
	v_lshlrev_b32_e32 v42, 16, v227
	v_and_b32_e32 v43, 0xffff0000, v227
	v_pk_fma_f32 v[34:35], v[126:127], v[38:39], v[34:35]
	v_pk_fma_f32 v[32:33], v[124:125], v[36:37], v[32:33]
	s_waitcnt lgkmcnt(0)
	v_pk_fma_f32 v[38:39], v[122:123], v[46:47], v[42:43]
	v_pk_fma_f32 v[36:37], v[120:121], v[44:45], v[40:41]
	global_store_dwordx4 v[56:57], v[32:35], off offset:512
	global_store_dwordx4 v[56:57], v[36:39], off offset:528
	s_nop 0
	ds_bpermute_b32 v36, v184, v24
	ds_bpermute_b32 v37, v184, v25
	ds_bpermute_b32 v38, v184, v26
	ds_bpermute_b32 v39, v184, v27
	v_lshl_add_u64 v[40:41], v[178:179], 0, v[156:157]
	s_waitcnt vmcnt(19)
	v_lshlrev_b32_e32 v24, 16, v228
	v_and_b32_e32 v25, 0xffff0000, v228
	v_lshlrev_b32_e32 v26, 16, v229
	v_and_b32_e32 v27, 0xffff0000, v229
	v_lshlrev_b32_e32 v32, 16, v230
	v_and_b32_e32 v33, 0xffff0000, v230
	v_lshlrev_b32_e32 v34, 16, v231
	v_and_b32_e32 v35, 0xffff0000, v231
	v_pk_fma_f32 v[26:27], v[134:135], v[30:31], v[26:27]
	v_pk_fma_f32 v[24:25], v[132:133], v[28:29], v[24:25]
	s_waitcnt lgkmcnt(0)
	v_pk_fma_f32 v[30:31], v[130:131], v[38:39], v[34:35]
	v_pk_fma_f32 v[28:29], v[128:129], v[36:37], v[32:33]
	global_store_dwordx4 v[40:41], v[24:27], off
	global_store_dwordx4 v[40:41], v[28:31], off offset:16
	s_nop 0
	ds_bpermute_b32 v28, v184, v16
	ds_bpermute_b32 v29, v184, v17
	ds_bpermute_b32 v30, v184, v18
	ds_bpermute_b32 v31, v184, v19
	v_lshl_add_u64 v[32:33], v[180:181], 0, v[174:175]
	s_waitcnt vmcnt(18)
	v_lshlrev_b32_e32 v16, 16, v232
	v_and_b32_e32 v17, 0xffff0000, v232
	v_lshlrev_b32_e32 v18, 16, v233
	v_and_b32_e32 v19, 0xffff0000, v233
	v_lshlrev_b32_e32 v24, 16, v234
	v_and_b32_e32 v25, 0xffff0000, v234
	v_lshlrev_b32_e32 v26, 16, v235
	v_and_b32_e32 v27, 0xffff0000, v235
	v_pk_fma_f32 v[18:19], v[126:127], v[22:23], v[18:19]
	v_pk_fma_f32 v[16:17], v[124:125], v[20:21], v[16:17]
	s_waitcnt lgkmcnt(0)
	v_pk_fma_f32 v[22:23], v[122:123], v[30:31], v[26:27]
	v_pk_fma_f32 v[20:21], v[120:121], v[28:29], v[24:25]
	global_store_dwordx4 v[40:41], v[16:19], off offset:512
	global_store_dwordx4 v[40:41], v[20:23], off offset:528
	s_nop 0
	ds_bpermute_b32 v20, v184, v8
	ds_bpermute_b32 v21, v184, v9
	ds_bpermute_b32 v22, v184, v10
	ds_bpermute_b32 v23, v184, v11
	v_lshl_add_u64 v[24:25], v[178:179], 0, v[158:159]
	s_waitcnt vmcnt(17)
	v_lshlrev_b32_e32 v8, 16, v236
	v_and_b32_e32 v9, 0xffff0000, v236
	v_lshlrev_b32_e32 v10, 16, v237
	v_and_b32_e32 v11, 0xffff0000, v237
	v_lshlrev_b32_e32 v16, 16, v238
	v_and_b32_e32 v17, 0xffff0000, v238
	v_lshlrev_b32_e32 v18, 16, v239
	v_and_b32_e32 v19, 0xffff0000, v239
	v_pk_fma_f32 v[10:11], v[134:135], v[14:15], v[10:11]
	v_pk_fma_f32 v[8:9], v[132:133], v[12:13], v[8:9]
	s_waitcnt lgkmcnt(0)
	v_pk_fma_f32 v[14:15], v[130:131], v[22:23], v[18:19]
	v_pk_fma_f32 v[12:13], v[128:129], v[20:21], v[16:17]
	global_store_dwordx4 v[24:25], v[8:11], off
	global_store_dwordx4 v[24:25], v[12:15], off offset:16
	s_nop 0
	ds_bpermute_b32 v12, v184, v0
	ds_bpermute_b32 v13, v184, v1
	ds_bpermute_b32 v14, v184, v2
	ds_bpermute_b32 v15, v184, v3
	s_waitcnt vmcnt(16)
	v_lshlrev_b32_e32 v0, 16, v240
	v_and_b32_e32 v1, 0xffff0000, v240
	v_lshlrev_b32_e32 v2, 16, v241
	v_and_b32_e32 v3, 0xffff0000, v241
	v_lshlrev_b32_e32 v8, 16, v242
	v_and_b32_e32 v9, 0xffff0000, v242
	v_lshlrev_b32_e32 v10, 16, v243
	v_and_b32_e32 v11, 0xffff0000, v243
	v_pk_fma_f32 v[2:3], v[126:127], v[6:7], v[2:3]
	v_pk_fma_f32 v[0:1], v[124:125], v[4:5], v[0:1]
	s_waitcnt lgkmcnt(0)
	v_pk_fma_f32 v[6:7], v[122:123], v[14:15], v[10:11]
	v_pk_fma_f32 v[4:5], v[120:121], v[12:13], v[8:9]
	global_store_dwordx4 v[24:25], v[0:3], off offset:512
	global_store_dwordx4 v[24:25], v[4:7], off offset:528
	s_cbranch_vccnz .LBB0_896
	s_andn2_b64 vcc, exec, s[10:11]
	s_cbranch_vccnz .LBB0_895
	s_barrier
	s_branch .LBB0_895
